# adds: stick-breaking loop with dead denormal/inf paths of the log expansion removed (bit-identical) and a real one-tile-ahead K/V prefetch
# baseline (speedup 1.0000x reference)
; __device__ __forceinline__ int otid() { int t = threadIdx.x; asm volatile("" : "+v"(t)); return t; }
; __device__ __forceinline__ void sb_load(SbFrags& F, const bf16_t* Pm, const bf16_t* VT, size_t tok0, int kv0, int h, int r32, int hi) {
;     const bf16_t* krow = Pm + (tok0 + kv0 + r32) * PW + PC_SBK + h * 64;
; #pragma unroll
;     for (int s = 0; s < 4; ++s) F.kf[s] = *(const bf16x8*)(krow + 16 * s + 8 * hi);
; #pragma unroll
;     for (int s = 0; s < 2; ++s) {
;         const bf16_t* v0p = VT + (size_t)(h * 64 + r32) * VTLD + tok0 + kv0 + 16 * s + 4 * hi; const bf16_t* v1p = v0p + (size_t)32 * VTLD;
;         F.v[4 * s + 0] = *(const s16x4*)v0p; F.v[4 * s + 1] = *(const s16x4*)(v0p + 8); F.v[4 * s + 2] = *(const s16x4*)v1p; F.v[4 * s + 3] = *(const s16x4*)(v1p + 8);
;     }
; template <bool DRY> __device__ __forceinline__ void sb_unit(int b, int h, int qi, bf16_t* Pm, const bf16_t* VT) {
;     const int lane = otid() & 63, r32 = lane & 31, hi = lane >> 5;
;     const size_t tok0 = (size_t)b * SEQ; const int q0 = qi * 32;
;     bf16_t* qrow = Pm + (tok0 + q0 + r32) * PW + PC_SBQ + h * 64;
;     bf16x8 qf[4];
; #pragma unroll
;     for (int s = 0; s < 4; ++s) qf[s] = *(const bf16x8*)(qrow + 16 * s + 8 * hi);
;     float R = 0.f; f32x16 o0 = {}, o1 = {};
;     SbFrags cur, nxt;
;     sb_load(cur, Pm, VT, tok0, qi * 32, h, r32, hi);
.LBB0_741:
	v_ashrrev_i32_e32 v4, 9, v3
	v_mov_b32_e32 v0, v234
	s_waitcnt vmcnt(0)
	v_and_b32_e32 v100, 63, v3
	v_ashrrev_i32_e32 v5, 31, v4
	v_and_b32_e32 v15, 31, v0
	v_bfe_u32 v16, v0, 5, 1
	v_lshlrev_b64 v[0:1], 11, v[4:5]
	v_lshlrev_b32_e32 v17, 5, v100
	v_or3_b32 v8, v15, v17, v0
	v_mov_b64_e32 v[6:7], s[42:43]
	v_and_b32_e32 v14, 0x1c0, v3
	v_mad_u64_u32 v[6:7], s[4:5], v8, s24, v[6:7]
	v_mad_i32_i24 v7, v1, s24, v7
	v_lshlrev_b32_e32 v8, 1, v14
	v_mov_b32_e32 v9, v2
	v_lshl_add_u64 v[84:85], v[6:7], 0, v[8:9]
	v_lshlrev_b32_e32 v10, 4, v16
	v_mov_b32_e32 v11, v2
	v_lshl_add_u64 v[12:13], v[84:85], 0, v[10:11]
	global_load_dwordx4 v[52:55], v[12:13], off offset:1280
	global_load_dwordx4 v[56:59], v[12:13], off offset:1312
	global_load_dwordx4 v[60:63], v[12:13], off offset:1344
	global_load_dwordx4 v[64:67], v[12:13], off offset:1376
	v_or_b32_e32 v12, v15, v14
	v_mul_u32_u24_e32 v12, 0x8200, v12
	v_lshlrev_b32_e32 v12, 1, v12
	v_mov_b32_e32 v13, v2
	v_lshl_add_u64 v[12:13], s[38:39], 0, v[12:13]
	v_lshlrev_b64 v[4:5], 12, v[4:5]
	v_lshlrev_b32_e32 v6, 3, v16
	v_mov_b32_e32 v7, v2
	v_lshl_add_u64 v[4:5], v[12:13], 0, v[4:5]
	v_lshlrev_b32_e32 v12, 6, v100
	v_mov_b32_e32 v13, v2
	v_lshl_add_u64 v[12:13], v[4:5], 0, v[12:13]
	v_lshl_add_u64 v[88:89], v[4:5], 0, v[6:7]
	v_xor_b32_e32 v4, 32, v238
	v_add_u32_e32 v5, 64, v239
	v_cmp_lt_i32_e32 vcc, v4, v5
	v_lshlrev_b32_e32 v86, 2, v16
	v_and_b32_e32 v98, 63, v87
	v_cndmask_b32_e32 v4, v238, v4, vcc
	v_lshlrev_b32_e32 v101, 2, v4
	v_or_b32_e32 v4, 1, v86
	v_cmp_lt_u32_e64 s[46:47], v4, v15
	v_or_b32_e32 v4, 2, v86
	v_cmp_lt_u32_e64 s[48:49], v4, v15
	v_or_b32_e32 v4, 3, v86
	v_cmp_lt_u32_e64 s[50:51], v4, v15
	v_or_b32_e32 v4, 8, v86
	v_cmp_lt_u32_e64 s[52:53], v4, v15
	v_or_b32_e32 v4, 9, v86
	v_cmp_lt_u32_e64 s[54:55], v4, v15
	v_or_b32_e32 v4, 10, v86
	v_cmp_lt_u32_e64 s[56:57], v4, v15
	v_or_b32_e32 v4, 11, v86
	v_cmp_lt_u32_e64 s[58:59], v4, v15
	v_or_b32_e32 v4, 16, v86
	v_cmp_lt_u32_e64 s[60:61], v4, v15
	v_or_b32_e32 v4, 17, v86
	v_cmp_lt_u32_e64 s[62:63], v4, v15
	v_or_b32_e32 v4, 18, v86
	v_cmp_lt_u32_e64 s[64:65], v4, v15
	v_or_b32_e32 v4, 19, v86
	v_cmp_lt_u32_e64 s[66:67], v4, v15
	v_or_b32_e32 v4, 24, v86
	v_cmp_lt_u32_e64 s[68:69], v4, v15
	v_or_b32_e32 v4, 25, v86
	v_cmp_lt_u32_e64 s[70:71], v4, v15
	v_or_b32_e32 v4, 26, v86
	v_cmp_lt_u32_e64 s[72:73], v4, v15
	v_or_b32_e32 v4, 27, v86
	v_or_b32_e32 v0, v0, v15
	v_cmp_lt_u32_e64 s[74:75], v4, v15
	v_lshl_add_u64 v[4:5], s[42:43], 0, v[8:9]
	v_mov_b32_e32 v102, 0
	v_lshlrev_b32_e32 v99, 5, v98
	v_or_b32_e32 v90, v0, v17
	v_mov_b32_e32 v91, v1
	v_lshl_add_u64 v[94:95], v[12:13], 0, v[6:7]
	s_mov_b32 s28, 0
	v_cmp_eq_u32_e64 s[12:13], 0, v16
	v_cmp_lt_u32_e64 s[44:45], v86, v15
	v_lshl_add_u64 v[92:93], v[4:5], 0, v[10:11]
	s_mov_b64 s[34:35], 0
	v_mov_b32_e32 v4, 0
	v_mov_b32_e32 v5, v102
	v_mov_b32_e32 v6, v102
	v_mov_b32_e32 v7, v102
	v_mov_b32_e32 v8, v102
	v_mov_b32_e32 v9, v102
	v_mov_b32_e32 v10, v102
	v_mov_b32_e32 v11, v102
	v_mov_b32_e32 v12, v102
	v_mov_b32_e32 v13, v102
	v_mov_b32_e32 v14, v102
	v_mov_b32_e32 v15, v102
	v_mov_b32_e32 v16, v102
	v_mov_b32_e32 v17, v102
	v_mov_b32_e32 v18, v102
	v_mov_b32_e32 v19, v102
	v_mov_b32_e32 v20, 0
	v_mov_b32_e32 v21, v102
	v_mov_b32_e32 v22, v102
	v_mov_b32_e32 v23, v102
	v_mov_b32_e32 v24, v102
	v_mov_b32_e32 v25, v102
	v_mov_b32_e32 v26, v102
	v_mov_b32_e32 v27, v102
	v_mov_b32_e32 v28, v102
	v_mov_b32_e32 v29, v102
	v_mov_b32_e32 v30, v102
	v_mov_b32_e32 v31, v102
	v_mov_b32_e32 v32, v102
	v_mov_b32_e32 v33, v102
	v_mov_b32_e32 v34, v102
	v_mov_b32_e32 v35, v102
	v_med3_i32 v36, v100, 0, 1
	v_lshlrev_b32_e32 v36, 5, v36
	s_mov_b32 s4, 0x208000
	v_sub_u32_e32 v40, v99, v36
	v_add_co_u32_e32 v36, vcc, s4, v94
	v_mov_b32_e32 v41, v2
	s_nop 0
	v_addc_co_u32_e32 v37, vcc, 0, v95, vcc
	global_load_dwordx2 v[70:71], v[36:37], off offset:48
	global_load_dwordx2 v[68:69], v[36:37], off offset:32
	global_load_dwordx2 v[74:75], v[94:95], off offset:48
	global_load_dwordx2 v[72:73], v[94:95], off offset:32
	global_load_dwordx2 v[78:79], v[36:37], off offset:16
	global_load_dwordx2 v[76:77], v[36:37], off
	global_load_dwordx2 v[82:83], v[94:95], off offset:16
	global_load_dwordx2 v[80:81], v[94:95], off
	v_mad_u64_u32 v[36:37], s[4:5], v90, s24, v[92:93]
	v_mov_b32_e32 v38, v37
	v_mad_u64_u32 v[38:39], s[4:5], v91, s24, v[38:39]
	v_mov_b32_e32 v37, v38
	global_load_dwordx4 v[104:107], v[36:37], off offset:2400
	global_load_dwordx4 v[108:111], v[36:37], off offset:2368
	global_load_dwordx4 v[112:115], v[36:37], off offset:2336
	s_nop 0
	global_load_dwordx4 v[136:139], v[36:37], off offset:2304
	v_lshl_add_u64 v[90:91], v[0:1], 0, v[40:41]
	v_lshl_add_u64 v[94:95], v[40:41], 1, v[88:89]
	v_add_u32_e32 v100, -1, v100
	v_subrev_u32_e32 v99, 32, v99
; __device__ __forceinline__ int crow(int r, int hi) { return (r & 3) + 8 * (r >> 2) + 4 * hi; }
; __device__ __forceinline__ void sb_load(SbFrags& F, const bf16_t* Pm, const bf16_t* VT, size_t tok0, int kv0, int h, int r32, int hi) {
;     const bf16_t* krow = Pm + (tok0 + kv0 + r32) * PW + PC_SBK + h * 64;
; #pragma unroll
;     for (int s = 0; s < 4; ++s) F.kf[s] = *(const bf16x8*)(krow + 16 * s + 8 * hi);
; #pragma unroll
;     for (int s = 0; s < 2; ++s) {
;         const bf16_t* v0p = VT + (size_t)(h * 64 + r32) * VTLD + tok0 + kv0 + 16 * s + 4 * hi; const bf16_t* v1p = v0p + (size_t)32 * VTLD;
;         F.v[4 * s + 0] = *(const s16x4*)v0p; F.v[4 * s + 1] = *(const s16x4*)(v0p + 8); F.v[4 * s + 2] = *(const s16x4*)v1p; F.v[4 * s + 3] = *(const s16x4*)(v1p + 8);
;     }
; template <bool DRY> __device__ __forceinline__ void sb_unit(int b, int h, int qi, bf16_t* Pm, const bf16_t* VT) {
;     ...
;         sb_load(nxt, Pm, VT, tok0, (kt > 0 ? kt - 1 : 0) * 32, h, r32, hi);
;         f32x16 p = {};
; #pragma unroll
;         for (int s = 0; s < 4; ++s) p = __builtin_amdgcn_mfma_f32_32x32x16_bf16(cur.kf[s], qf[s], p, 0, 0, 0);
;         const bool diag = (kt == qi);
;         float lk[16], inner[16], Tg[4], TP[4], pre[4];
; #pragma unroll
;         for (int r = 0; r < 16; ++r) {
;             const float z = p[r] * 0.125f; p[r] = z;
;             const float e = __expf(-fabsf(z)); const float sp = fmaxf(z, 0.f) + __logf(1.f + e);
;             const bool valid = !diag || (crow(r, hi) < r32);
;             lk[r] = valid ? -sp : 0.f;
.LBB0_742:
	v_med3_i32 v36, v100, 0, 1
	v_lshlrev_b32_e32 v36, 5, v36
	s_mov_b32 s4, 0x208000
	v_sub_u32_e32 v40, v99, v36
	v_add_co_u32_e32 v36, vcc, s4, v94
	v_mov_b32_e32 v41, v2
	s_nop 0
	v_addc_co_u32_e32 v37, vcc, 0, v95, vcc
	global_load_dwordx2 v[158:159], v[36:37], off offset:48
	global_load_dwordx2 v[156:157], v[36:37], off offset:32
	global_load_dwordx2 v[162:163], v[94:95], off offset:48
	global_load_dwordx2 v[160:161], v[94:95], off offset:32
	global_load_dwordx2 v[166:167], v[36:37], off offset:16
	global_load_dwordx2 v[164:165], v[36:37], off
	global_load_dwordx2 v[170:171], v[94:95], off offset:16
	global_load_dwordx2 v[168:169], v[94:95], off
	v_mad_u64_u32 v[36:37], s[4:5], v90, s24, v[92:93]
	v_mov_b32_e32 v38, v37
	v_mad_u64_u32 v[38:39], s[4:5], v91, s24, v[38:39]
	v_mov_b32_e32 v37, v38
	global_load_dwordx4 v[152:155], v[36:37], off offset:2400
	global_load_dwordx4 v[148:151], v[36:37], off offset:2368
	global_load_dwordx4 v[144:147], v[36:37], off offset:2336
	s_nop 0
	global_load_dwordx4 v[140:143], v[36:37], off offset:2304
	v_lshl_add_u64 v[90:91], v[0:1], 0, v[40:41]
	v_lshl_add_u64 v[94:95], v[40:41], 1, v[88:89]
	s_cmp_lg_u32 s28, 0
	s_cselect_b64 s[22:23], -1, 0
	s_or_b64 s[76:77], s[44:45], s[22:23]
	s_or_b64 s[78:79], s[46:47], s[22:23]
	s_or_b64 s[80:81], s[48:49], s[22:23]
	s_or_b64 s[88:89], s[56:57], s[22:23]
	s_or_b64 s[94:95], s[62:63], s[22:23]
	s_or_b64 s[96:97], s[64:65], s[22:23]
	s_or_b64 s[84:85], s[52:53], s[22:23]
	s_or_b64 s[86:87], s[54:55], s[22:23]
	s_or_b64 s[92:93], s[60:61], s[22:23]
	s_or_b64 s[90:91], s[58:59], s[22:23]
	s_or_b64 s[82:83], s[50:51], s[22:23]
	v_add_u32_e32 v100, -1, v100
	v_subrev_u32_e32 v99, 32, v99
	s_waitcnt vmcnt(12)
	v_mfma_f32_32x32x16_bf16 v[36:51], v[136:139], v[52:55], 0
	v_mfma_f32_32x32x16_bf16 v[36:51], v[112:115], v[56:59], v[36:51]
	v_mfma_f32_32x32x16_bf16 v[36:51], v[108:111], v[60:63], v[36:51]
	v_mfma_f32_32x32x16_bf16 v[36:51], v[104:107], v[64:67], v[36:51]
	s_nop 11
	v_mul_f32_e32 v96, 0x3e000000, v36
	v_mul_f32_e64 v97, |v96|, s25
	v_exp_f32_e32 v97, v97
	v_max_f32_e32 v96, 0, v96
	v_add_f32_e32 v97, 1.0, v97
	v_log_f32_e32 v97, v97
	s_nop 0
	v_mul_f32_e32 v103, 0x3f317217, v97
	v_fma_f32 v103, v97, s19, -v103
	v_fmac_f32_e32 v103, 0x3377d1cf, v97
	v_fmac_f32_e32 v103, 0x3f317217, v97
	v_mov_b32_e32 v97, v103
	v_add_f32_e32 v96, v96, v97
	v_cndmask_b32_e64 v103, 0, -v96, s[76:77]
	v_mul_f32_e32 v96, 0x3e000000, v37
	v_mul_f32_e64 v97, |v96|, s25
	v_exp_f32_e32 v97, v97
	v_max_f32_e32 v96, 0, v96
	v_fmamk_f32 v36, v36, 0x3e000000, v103
	v_add_f32_e32 v97, 1.0, v97
	v_log_f32_e32 v97, v97
	s_nop 0
	v_mul_f32_e32 v104, 0x3f317217, v97
	v_fma_f32 v104, v97, s19, -v104
	v_fmac_f32_e32 v104, 0x3377d1cf, v97
	v_fmac_f32_e32 v104, 0x3f317217, v97
	v_mov_b32_e32 v97, v104
	v_add_f32_e32 v96, v96, v97
	v_cndmask_b32_e64 v108, 0, -v96, s[78:79]
	v_mul_f32_e32 v96, 0x3e000000, v38
	v_mul_f32_e64 v97, |v96|, s25
	v_exp_f32_e32 v97, v97
	v_max_f32_e32 v96, 0, v96
	v_add_f32_e32 v97, 1.0, v97
	v_log_f32_e32 v97, v97
	s_nop 0
	v_mul_f32_e32 v104, 0x3f317217, v97
	v_fma_f32 v104, v97, s19, -v104
	v_fmac_f32_e32 v104, 0x3377d1cf, v97
	v_fmac_f32_e32 v104, 0x3f317217, v97
	v_mov_b32_e32 v97, v104
	v_add_f32_e32 v96, v96, v97
	v_cndmask_b32_e64 v109, 0, -v96, s[80:81]
	v_mul_f32_e32 v96, 0x3e000000, v39
	v_mul_f32_e64 v39, |v96|, s25
	v_exp_f32_e32 v39, v39
	v_max_f32_e32 v97, 0, v96
	v_add_f32_e32 v39, 1.0, v39
	v_log_f32_e32 v39, v39
	s_nop 0
	v_mul_f32_e32 v104, 0x3f317217, v39
	v_fma_f32 v104, v39, s19, -v104
	v_fmac_f32_e32 v104, 0x3377d1cf, v39
	v_fmac_f32_e32 v104, 0x3f317217, v39
	v_mov_b32_e32 v39, v104
	v_add_f32_e32 v110, v97, v39
	v_mul_f32_e32 v39, 0x3e000000, v40
	v_mul_f32_e64 v97, |v39|, s25
	v_exp_f32_e32 v97, v97
	v_max_f32_e32 v39, 0, v39
	v_add_f32_e32 v97, 1.0, v97
	v_log_f32_e32 v97, v97
	s_nop 0
	v_mul_f32_e32 v104, 0x3f317217, v97
	v_fma_f32 v104, v97, s19, -v104
	v_fmac_f32_e32 v104, 0x3377d1cf, v97
	v_fmac_f32_e32 v104, 0x3f317217, v97
	v_mov_b32_e32 v97, v104
	v_add_f32_e32 v39, v39, v97
	v_mul_f32_e32 v97, 0x3e000000, v41
	v_mul_f32_e64 v104, |v97|, s25
	v_exp_f32_e32 v104, v104
	v_max_f32_e32 v97, 0, v97
	v_cndmask_b32_e64 v39, 0, -v39, s[84:85]
	v_add_f32_e32 v104, 1.0, v104
	v_log_f32_e32 v104, v104
	s_nop 0
	v_mul_f32_e32 v105, 0x3f317217, v104
	v_fma_f32 v105, v104, s19, -v105
	v_fmac_f32_e32 v105, 0x3377d1cf, v104
	v_fmac_f32_e32 v105, 0x3f317217, v104
	v_mov_b32_e32 v104, v105
	v_add_f32_e32 v97, v97, v104
	v_mul_f32_e32 v104, 0x3e000000, v42
	v_mul_f32_e64 v105, |v104|, s25
	v_exp_f32_e32 v105, v105
	v_max_f32_e32 v104, 0, v104
	v_cndmask_b32_e64 v97, 0, -v97, s[86:87]
	v_add_f32_e32 v105, 1.0, v105
	v_log_f32_e32 v105, v105
	s_nop 0
	v_mul_f32_e32 v106, 0x3f317217, v105
	v_fma_f32 v106, v105, s19, -v106
	v_fmac_f32_e32 v106, 0x3377d1cf, v105
	v_fmac_f32_e32 v106, 0x3f317217, v105
	v_mov_b32_e32 v105, v106
	v_add_f32_e32 v104, v104, v105
	v_cndmask_b32_e64 v111, 0, -v104, s[88:89]
	v_mul_f32_e32 v104, 0x3e000000, v43
	v_mul_f32_e64 v43, |v104|, s25
	v_exp_f32_e32 v43, v43
	v_max_f32_e32 v105, 0, v104
	v_add_f32_e32 v43, 1.0, v43
	v_log_f32_e32 v43, v43
	s_nop 0
	v_mul_f32_e32 v106, 0x3f317217, v43
	v_fma_f32 v106, v43, s19, -v106
	v_fmac_f32_e32 v106, 0x3377d1cf, v43
	v_fmac_f32_e32 v106, 0x3f317217, v43
	v_mov_b32_e32 v43, v106
	v_add_f32_e32 v43, v105, v43
	v_mul_f32_e32 v105, 0x3e000000, v44
	v_mul_f32_e64 v106, |v105|, s25
	v_exp_f32_e32 v106, v106
	v_max_f32_e32 v105, 0, v105
	v_add_f32_e32 v106, 1.0, v106
	v_log_f32_e32 v106, v106
	s_nop 0
	v_mul_f32_e32 v107, 0x3f317217, v106
	v_fma_f32 v107, v106, s19, -v107
; __device__ __forceinline__ int crow(int r, int hi) { return (r & 3) + 8 * (r >> 2) + 4 * hi; }
; template <bool DRY> __device__ __forceinline__ void sb_unit(int b, int h, int qi, bf16_t* Pm, const bf16_t* VT) {
;     ...
;         for (int r = 0; r < 16; ++r) {
;             const float z = p[r] * 0.125f; p[r] = z;
;             const float e = __expf(-fabsf(z)); const float sp = fmaxf(z, 0.f) + __logf(1.f + e);
;             const bool valid = !diag || (crow(r, hi) < r32);
;             lk[r] = valid ? -sp : 0.f;
;         }
; #pragma unroll
;         for (int g = 0; g < 4; ++g) {
;             const float s3 = lk[4 * g + 3], s2 = s3 + lk[4 * g + 2], s1 = s2 + lk[4 * g + 1];
;             inner[4 * g + 3] = 0.f; inner[4 * g + 2] = s3; inner[4 * g + 1] = s2; inner[4 * g] = s1; Tg[g] = s1 + lk[4 * g];
;             TP[g] = __shfl_xor(Tg[g], 32);
;         }
;         float run = 0.f;
; #pragma unroll
;         for (int g = 3; g >= 0; --g) { pre[g] = run + (hi == 0 ? TP[g] : 0.f); run += Tg[g] + TP[g]; }
	v_fmac_f32_e32 v107, 0x3377d1cf, v106
	v_fmac_f32_e32 v107, 0x3f317217, v106
	v_mov_b32_e32 v106, v107
	v_add_f32_e32 v105, v105, v106
	v_mul_f32_e32 v106, 0x3e000000, v45
	v_mul_f32_e64 v107, |v106|, s25
	v_exp_f32_e32 v107, v107
	v_max_f32_e32 v106, 0, v106
	v_cndmask_b32_e64 v105, 0, -v105, s[92:93]
	v_add_f32_e32 v107, 1.0, v107
	v_log_f32_e32 v107, v107
	s_nop 0
	v_mul_f32_e32 v112, 0x3f317217, v107
	v_fma_f32 v112, v107, s19, -v112
	v_fmac_f32_e32 v112, 0x3377d1cf, v107
	v_fmac_f32_e32 v112, 0x3f317217, v107
	v_mov_b32_e32 v107, v112
	v_add_f32_e32 v106, v106, v107
	v_cndmask_b32_e64 v112, 0, -v106, s[94:95]
	v_mul_f32_e32 v106, 0x3e000000, v46
	v_mul_f32_e64 v107, |v106|, s25
	v_exp_f32_e32 v107, v107
	v_max_f32_e32 v106, 0, v106
	v_add_f32_e32 v107, 1.0, v107
	v_log_f32_e32 v107, v107
	s_nop 0
	v_mul_f32_e32 v113, 0x3f317217, v107
	v_fma_f32 v113, v107, s19, -v113
	v_fmac_f32_e32 v113, 0x3377d1cf, v107
	v_fmac_f32_e32 v113, 0x3f317217, v107
	v_mov_b32_e32 v107, v113
	v_add_f32_e32 v106, v106, v107
	v_cndmask_b32_e64 v113, 0, -v106, s[96:97]
	v_mul_f32_e32 v106, 0x3e000000, v47
	v_mul_f32_e64 v47, |v106|, s25
	v_exp_f32_e32 v47, v47
	v_max_f32_e32 v107, 0, v106
	v_add_f32_e32 v47, 1.0, v47
	v_log_f32_e32 v47, v47
	s_nop 0
	v_mul_f32_e32 v114, 0x3f317217, v47
	v_fma_f32 v114, v47, s19, -v114
	v_fmac_f32_e32 v114, 0x3377d1cf, v47
	v_fmac_f32_e32 v114, 0x3f317217, v47
	v_mov_b32_e32 v47, v114
	v_add_f32_e32 v47, v107, v47
	v_mul_f32_e32 v107, 0x3e000000, v48
	v_mul_f32_e64 v114, |v107|, s25
	v_exp_f32_e32 v114, v114
	v_max_f32_e32 v107, 0, v107
	s_or_b64 s[4:5], s[66:67], s[22:23]
	v_add_f32_e32 v114, 1.0, v114
	v_log_f32_e32 v114, v114
	s_nop 0
	v_mul_f32_e32 v115, 0x3f317217, v114
	v_fma_f32 v115, v114, s19, -v115
	v_fmac_f32_e32 v115, 0x3377d1cf, v114
	v_fmac_f32_e32 v115, 0x3f317217, v114
	v_mov_b32_e32 v114, v115
	v_add_f32_e32 v107, v107, v114
	s_or_b64 s[6:7], s[68:69], s[22:23]
	v_cndmask_b32_e64 v114, 0, -v107, s[6:7]
	v_mul_f32_e32 v107, 0x3e000000, v49
	v_mul_f32_e64 v115, |v107|, s25
	v_exp_f32_e32 v115, v115
	v_max_f32_e32 v107, 0, v107
	v_add_f32_e32 v115, 1.0, v115
	v_log_f32_e32 v115, v115
	s_nop 0
	v_mul_f32_e32 v116, 0x3f317217, v115
	v_fma_f32 v116, v115, s19, -v116
	v_fmac_f32_e32 v116, 0x3377d1cf, v115
	v_fmac_f32_e32 v116, 0x3f317217, v115
	v_mov_b32_e32 v115, v116
	v_add_f32_e32 v107, v107, v115
	s_or_b64 s[8:9], s[70:71], s[22:23]
	v_cndmask_b32_e64 v115, 0, -v107, s[8:9]
	v_mul_f32_e32 v107, 0x3e000000, v50
	v_mul_f32_e64 v116, |v107|, s25
	v_exp_f32_e32 v116, v116
	v_max_f32_e32 v107, 0, v107
	v_add_f32_e32 v116, 1.0, v116
	v_log_f32_e32 v116, v116
	s_nop 0
	v_mul_f32_e32 v117, 0x3f317217, v116
	v_fma_f32 v117, v116, s19, -v117
	v_fmac_f32_e32 v117, 0x3377d1cf, v116
	v_fmac_f32_e32 v117, 0x3f317217, v116
	v_mov_b32_e32 v116, v117
	v_add_f32_e32 v107, v107, v116
	s_or_b64 s[10:11], s[72:73], s[22:23]
	v_cndmask_b32_e64 v116, 0, -v107, s[10:11]
	v_mul_f32_e32 v107, 0x3e000000, v51
	v_mul_f32_e64 v117, |v107|, s25
	v_exp_f32_e32 v117, v117
	v_max_f32_e32 v107, 0, v107
	v_add_f32_e32 v117, 1.0, v117
	v_log_f32_e32 v117, v117
	s_nop 0
	v_mul_f32_e32 v118, 0x3f317217, v117
	v_fma_f32 v118, v117, s19, -v118
	v_fmac_f32_e32 v118, 0x3377d1cf, v117
	v_fmac_f32_e32 v118, 0x3f317217, v117
	v_mov_b32_e32 v117, v118
	v_add_f32_e32 v107, v107, v117
	s_or_b64 vcc, s[74:75], s[22:23]
	v_cndmask_b32_e64 v117, 0, -v107, vcc
	v_add_f32_e32 v118, v117, v116
	v_add_f32_e32 v119, v115, v118
	v_add_f32_e32 v107, v114, v119
	ds_bpermute_b32 v120, v101, v107
	v_fmac_f32_e32 v114, 0x3e000000, v48
	v_fmac_f32_e32 v115, 0x3e000000, v49
	v_fmac_f32_e32 v116, 0x3e000000, v50
	s_waitcnt lgkmcnt(0)
	v_add_f32_e32 v121, 0, v120
	v_add_f32_e32 v107, v107, v120
	v_add_f32_e32 v120, v102, v36
	v_fmamk_f32 v36, v37, 0x3e000000, v108
	v_add_f32_e32 v122, v102, v36
	v_fmamk_f32 v36, v38, 0x3e000000, v109
	v_add_f32_e32 v123, v102, v36
	v_fmamk_f32 v36, v40, 0x3e000000, v39
	v_add_f32_e32 v124, v102, v36
	v_fmamk_f32 v36, v41, 0x3e000000, v97
	v_add_f32_e32 v125, v102, v36
	v_fmamk_f32 v36, v42, 0x3e000000, v111
	v_add_f32_e32 v126, v102, v36
	v_fmamk_f32 v36, v44, 0x3e000000, v105
	v_add_f32_e32 v127, v102, v36
	v_fmamk_f32 v36, v45, 0x3e000000, v112
	v_add_f32_e32 v128, v102, v36
	v_fmamk_f32 v36, v46, 0x3e000000, v113
	v_add_f32_e32 v46, v102, v36
	v_cndmask_b32_e64 v36, 0, -v47, s[4:5]
	v_add_f32_e32 v47, v36, v113
	v_add_f32_e32 v112, v112, v47
	v_add_f32_e32 v38, v105, v112
	ds_bpermute_b32 v40, v101, v38
	v_add_f32_e32 v107, 0, v107
	v_cndmask_b32_e64 v121, 0, v121, s[12:13]
	s_waitcnt lgkmcnt(0)
	v_add_f32_e32 v38, v38, v40
	v_add_f32_e32 v105, v38, v107
	v_cndmask_b32_e64 v38, 0, -v43, s[90:91]
	v_add_f32_e32 v111, v38, v111
	v_add_f32_e32 v113, v97, v111
	v_cndmask_b32_e64 v37, 0, v40, s[12:13]
	v_add_f32_e32 v40, v39, v113
	ds_bpermute_b32 v41, v101, v40
	s_waitcnt lgkmcnt(0)
	v_cndmask_b32_e64 v39, 0, v41, s[12:13]
	v_add_f32_e32 v42, v40, v41
	v_pk_add_f32 v[40:41], v[104:105], v[38:39]
	v_add_f32_e32 v97, v42, v105
	v_cndmask_b32_e64 v42, 0, -v110, s[82:83]
	v_add_f32_e32 v39, v102, v40
	v_add_f32_e32 v40, v42, v109
	v_add_f32_e32 v104, v108, v40
	v_add_f32_e32 v44, v103, v104
	ds_bpermute_b32 v45, v101, v44
	s_waitcnt lgkmcnt(0)
; __device__ __forceinline__ unsigned cvtpk(float lo, float hi) { f32x2_t v = {lo, hi}; bf16x2_t b = __builtin_convertvector(v, bf16x2_t); return __builtin_bit_cast(unsigned, b); }
; __device__ __forceinline__ int crow(int r, int hi) { return (r & 3) + 8 * (r >> 2) + 4 * hi; }
; template <bool DRY> __device__ __forceinline__ void sb_unit(int b, int h, int qi, bf16_t* Pm, const bf16_t* VT) {
;     ...
;         for (int r = 0; r < 16; ++r) {
;             const bool valid = !diag || (crow(r, hi) < r32);
;             const float ex = fminf(p[r] + lk[r] + R + pre[r >> 2] + inner[r], 0.f);
;             p[r] = valid ? __expf(ex) : 0.f;
;         }
;         R += run;
; #pragma unroll
;         for (int s = 0; s < 2; ++s) {
;             const u32x4 pw = (u32x4){cvtpk(p[8 * s + 0], p[8 * s + 1]), cvtpk(p[8 * s + 2], p[8 * s + 3]), cvtpk(p[8 * s + 4], p[8 * s + 5]), cvtpk(p[8 * s + 6], p[8 * s + 7])};
;             const bf16x8 pf = __builtin_bit_cast(bf16x8, pw);
;             const s16x4 l0 = cur.v[4 * s], h0 = cur.v[4 * s + 1], l1 = cur.v[4 * s + 2], h1 = cur.v[4 * s + 3];
;             const bf16x8 v0 = (bf16x8){l0[0], l0[1], l0[2], l0[3], h0[0], h0[1], h0[2], h0[3]};
;             const bf16x8 v1 = (bf16x8){l1[0], l1[1], l1[2], l1[3], h1[0], h1[1], h1[2], h1[3]};
;             o0 = __builtin_amdgcn_mfma_f32_32x32x16_bf16(v0, pf, o0, 0, 0, 0);
;             o1 = __builtin_amdgcn_mfma_f32_32x32x16_bf16(v1, pf, o1, 0, 0, 0);
;         }
;         if (__all(R < -104.f)) break;
;         cur = nxt;
;     }
; #pragma unroll
;     for (int g = 0; g < 4; ++g) {
;         u32x2 w0, w1;
;         w0.x = cvtpk(o0[4 * g], o0[4 * g + 1]); w0.y = cvtpk(o0[4 * g + 2], o0[4 * g + 3]);
;         w1.x = cvtpk(o1[4 * g], o1[4 * g + 1]); w1.y = cvtpk(o1[4 * g + 2], o1[4 * g + 3]);
;         if (!DRY || R == 1234.56789f) { *(u32x2*)(qrow + 8 * g + 4 * hi) = w0; *(u32x2*)(qrow + 32 + 8 * g + 4 * hi) = w1; }
;     }
	v_cndmask_b32_e64 v43, 0, v45, s[12:13]
	v_add_f32_e32 v103, v44, v45
	v_pk_add_f32 v[44:45], v[96:97], v[42:43]
	v_add_f32_e32 v97, v103, v97
	v_add_f32_e32 v43, v102, v44
	v_add_f32_e32 v44, v120, v45
	v_add_f32_e32 v44, v104, v44
	v_add_f32_e32 v104, v126, v41
	v_add_f32_e32 v38, v38, v104
	v_min_f32_e32 v38, 0, v38
	v_mul_f32_e32 v38, 0x3fb8aa3b, v38
	v_exp_f32_e32 v38, v38
	v_add_f32_e32 v96, v122, v45
	v_add_f32_e32 v40, v40, v96
	v_add_f32_e32 v96, v123, v45
	v_cndmask_b32_e64 v104, 0, v38, s[88:89]
	v_add_f32_e32 v38, v39, v41
	v_min_f32_e32 v38, 0, v38
	v_mul_f32_e32 v38, 0x3fb8aa3b, v38
	v_exp_f32_e32 v38, v38
	v_add_f32_e32 v42, v42, v96
	v_add_f32_e32 v43, v43, v45
	v_add_f32_e32 v45, v124, v41
	v_add_f32_e32 v96, v125, v41
	v_cndmask_b32_e64 v41, 0, v38, s[90:91]
	v_pk_add_f32 v[38:39], v[106:107], v[36:37]
	v_add_f32_e32 v45, v113, v45
	v_add_f32_e32 v37, v127, v39
	v_add_f32_e32 v37, v112, v37
	v_min_f32_e32 v37, 0, v37
	v_mul_f32_e32 v37, 0x3fb8aa3b, v37
	v_exp_f32_e32 v37, v37
	v_add_f32_e32 v96, v111, v96
	v_min_f32_e32 v44, 0, v44
	v_min_f32_e32 v40, 0, v40
	v_cndmask_b32_e64 v105, 0, v37, s[92:93]
	v_add_f32_e32 v37, v128, v39
	v_add_f32_e32 v37, v47, v37
	v_min_f32_e32 v37, 0, v37
	v_mul_f32_e32 v37, 0x3fb8aa3b, v37
	v_exp_f32_e32 v37, v37
	v_min_f32_e32 v42, 0, v42
	v_min_f32_e32 v43, 0, v43
	v_min_f32_e32 v45, 0, v45
	v_cndmask_b32_e64 v47, 0, v37, s[94:95]
	v_add_f32_e32 v37, v46, v39
	v_add_f32_e32 v36, v36, v37
	v_min_f32_e32 v36, 0, v36
	v_mul_f32_e32 v36, 0x3fb8aa3b, v36
	v_exp_f32_e32 v36, v36
	v_min_f32_e32 v96, 0, v96
	v_mul_f32_e32 v44, 0x3fb8aa3b, v44
	v_mul_f32_e32 v40, 0x3fb8aa3b, v40
	v_cndmask_b32_e64 v46, 0, v36, s[96:97]
	v_add_f32_e32 v36, v102, v38
	v_add_f32_e32 v36, v36, v39
	v_min_f32_e32 v36, 0, v36
	v_mul_f32_e32 v36, 0x3fb8aa3b, v36
	v_exp_f32_e32 v36, v36
	v_mul_f32_e32 v42, 0x3fb8aa3b, v42
	v_mul_f32_e32 v43, 0x3fb8aa3b, v43
	v_mul_f32_e32 v45, 0x3fb8aa3b, v45
	v_cndmask_b32_e64 v106, 0, v36, s[4:5]
	v_add_f32_e32 v36, v102, v114
	v_add_f32_e32 v36, v121, v36
	v_add_f32_e32 v36, v119, v36
	v_min_f32_e32 v36, 0, v36
	v_mul_f32_e32 v36, 0x3fb8aa3b, v36
	v_exp_f32_e32 v36, v36
	v_mul_f32_e32 v96, 0x3fb8aa3b, v96
	v_exp_f32_e32 v44, v44
	v_exp_f32_e32 v40, v40
	v_cndmask_b32_e64 v48, 0, v36, s[6:7]
	v_add_f32_e32 v36, v102, v115
	v_add_f32_e32 v36, v121, v36
	v_add_f32_e32 v36, v118, v36
	v_min_f32_e32 v36, 0, v36
	v_mul_f32_e32 v36, 0x3fb8aa3b, v36
	v_exp_f32_e32 v36, v36
	v_exp_f32_e32 v42, v42
	v_exp_f32_e32 v43, v43
	v_exp_f32_e32 v45, v45
	v_cndmask_b32_e64 v49, 0, v36, s[8:9]
	v_add_f32_e32 v36, v102, v116
	v_add_f32_e32 v36, v121, v36
	v_add_f32_e32 v36, v117, v36
	v_min_f32_e32 v36, 0, v36
	v_mul_f32_e32 v36, 0x3fb8aa3b, v36
	v_exp_f32_e32 v36, v36
	v_fmac_f32_e32 v117, 0x3e000000, v51
	v_exp_f32_e32 v96, v96
	v_cndmask_b32_e64 v44, 0, v44, s[76:77]
	v_cndmask_b32_e64 v50, 0, v36, s[10:11]
	v_add_f32_e32 v36, v102, v117
	v_add_f32_e32 v36, v121, v36
	v_min_f32_e32 v36, 0, v36
	v_mul_f32_e32 v36, 0x3fb8aa3b, v36
	v_exp_f32_e32 v36, v36
	v_cndmask_b32_e64 v40, 0, v40, s[78:79]
	v_cndmask_b32_e64 v42, 0, v42, s[80:81]
	v_cndmask_b32_e64 v43, 0, v43, s[82:83]
	v_cndmask_b32_e64 v45, 0, v45, s[84:85]
	v_cndmask_b32_e64 v96, 0, v96, s[86:87]
	v_cndmask_b32_e32 v51, 0, v36, vcc
	v_cvt_pk_bf16_f32 v36, v44, v40
	v_cvt_pk_bf16_f32 v37, v42, v43
	v_cvt_pk_bf16_f32 v38, v45, v96
	v_cvt_pk_bf16_f32 v39, v104, v41
	v_add_f32_e32 v102, v102, v97
	s_mov_b32 s4, 0xc2d00000
	v_mfma_f32_32x32x16_bf16 v[4:19], v[80:83], v[36:39], v[4:19]
	v_cmp_gt_f32_e32 vcc, s4, v102
	s_cmp_eq_u64 vcc, exec
	s_cselect_b64 s[4:5], -1, 0
	v_cmp_eq_u32_e32 vcc, s28, v98
	s_or_b64 s[4:5], s[4:5], vcc
	s_add_i32 s28, s28, 1
	s_and_b64 s[4:5], exec, s[4:5]
	v_mfma_f32_32x32x16_bf16 v[20:35], v[76:79], v[36:39], v[20:35]
	v_cvt_pk_bf16_f32 v36, v105, v47
	v_cvt_pk_bf16_f32 v37, v46, v106
	v_cvt_pk_bf16_f32 v38, v48, v49
	v_cvt_pk_bf16_f32 v39, v50, v51
	s_or_b64 s[34:35], s[4:5], s[34:35]
	s_nop 0
	v_mfma_f32_32x32x16_bf16 v[4:19], v[72:75], v[36:39], v[4:19]
	v_mfma_f32_32x32x16_bf16 v[20:35], v[68:71], v[36:39], v[20:35]
	s_waitcnt vmcnt(0)
	v_mov_b32_e32 v136, v140
	v_mov_b32_e32 v137, v141
	v_mov_b32_e32 v138, v142
	v_mov_b32_e32 v139, v143
	v_mov_b32_e32 v112, v144
	v_mov_b32_e32 v113, v145
	v_mov_b32_e32 v114, v146
	v_mov_b32_e32 v115, v147
	v_mov_b32_e32 v108, v148
	v_mov_b32_e32 v109, v149
	v_mov_b32_e32 v110, v150
	v_mov_b32_e32 v111, v151
	v_mov_b32_e32 v104, v152
	v_mov_b32_e32 v105, v153
	v_mov_b32_e32 v106, v154
	v_mov_b32_e32 v107, v155
	v_mov_b32_e32 v68, v156
	v_mov_b32_e32 v69, v157
	v_mov_b32_e32 v70, v158
	v_mov_b32_e32 v71, v159
	v_mov_b32_e32 v72, v160
	v_mov_b32_e32 v73, v161
	v_mov_b32_e32 v74, v162
	v_mov_b32_e32 v75, v163
	v_mov_b32_e32 v76, v164
	v_mov_b32_e32 v77, v165
	v_mov_b32_e32 v78, v166
	v_mov_b32_e32 v79, v167
	v_mov_b32_e32 v80, v168
	v_mov_b32_e32 v81, v169
	v_mov_b32_e32 v82, v170
	v_mov_b32_e32 v83, v171
	s_andn2_b64 exec, exec, s[34:35]
	s_cbranch_execnz .LBB0_742
	s_or_b64 exec, exec, s[34:35]
	v_lshlrev_b32_e32 v0, 1, v86
	v_mov_b32_e32 v1, v2
	v_lshl_add_u64 v[0:1], v[84:85], 0, v[0:1]
	s_nop 4
	v_cvt_pk_bf16_f32 v4, v4, v5
	v_cvt_pk_bf16_f32 v5, v6, v7
	v_cvt_pk_bf16_f32 v6, v20, v21
	v_cvt_pk_bf16_f32 v7, v22, v23
	global_store_dwordx2 v[0:1], v[4:5], off offset:1280
	global_store_dwordx2 v[0:1], v[6:7], off offset:1344
	v_cvt_pk_bf16_f32 v4, v8, v9
	v_cvt_pk_bf16_f32 v5, v10, v11
	v_add_u32_e32 v3, s26, v3
	s_movk_i32 s4, 0x1fff
	v_cvt_pk_bf16_f32 v6, v24, v25
	v_cvt_pk_bf16_f32 v7, v26, v27
	global_store_dwordx2 v[0:1], v[4:5], off offset:1296
	global_store_dwordx2 v[0:1], v[6:7], off offset:1360
	v_cvt_pk_bf16_f32 v4, v12, v13
	v_cvt_pk_bf16_f32 v5, v14, v15
	v_cmp_lt_i32_e32 vcc, s4, v3
	v_cvt_pk_bf16_f32 v6, v28, v29
	v_cvt_pk_bf16_f32 v7, v30, v31
	global_store_dwordx2 v[0:1], v[4:5], off offset:1312
	global_store_dwordx2 v[0:1], v[6:7], off offset:1376
	v_cvt_pk_bf16_f32 v4, v16, v17
	v_cvt_pk_bf16_f32 v5, v18, v19
	s_or_b64 s[40:41], vcc, s[40:41]
	v_add_u16_e32 v87, s26, v87
	v_cvt_pk_bf16_f32 v6, v32, v33
	v_cvt_pk_bf16_f32 v7, v34, v35
	global_store_dwordx2 v[0:1], v[4:5], off offset:1328
	global_store_dwordx2 v[0:1], v[6:7], off offset:1392
	s_andn2_b64 exec, exec, s[40:41]
	s_cbranch_execnz .LBB0_741
